# register-resident final RMSNorm with the cross-lane reductions of all row groups batched
# baseline (speedup 1.0000x reference)
; __device__ __forceinline__ unsigned cvt_pk_bf16(float lo, float hi) { f32x2 v = {lo, hi}; bf16x2_t b = __builtin_convertvector(v, bf16x2_t); return __builtin_bit_cast(unsigned, b); }
;     __device__ __forceinline__ void operator()(const f32x4 (&acc)[2][2][4][2], const Unit& u, int wr, int wc, int fr, int fq) const {
;     ...
;                     for (int n = 0; n < 2; ++n) bs[m][bj][n] = *(const f32x4*)(base + (size_t)(row0 + ai * HALF + m * 16) * DMODEL + col0 + bj * HALF + n * 16);
; #pragma unroll
;             for (int m = 0; m < 4; ++m) { const int row = row0 + ai * HALF + m * 16; const size_t off = (size_t)row * DMODEL + col0; float sq = 0.f;
; #pragma unroll
;                 for (int bj = 0; bj < 2; ++bj)
; #pragma unroll
;                     for (int n = 0; n < 2; ++n) { const size_t o2 = off + bj * HALF + n * 16; const f32x4 o = bs[m][bj][n] + acc[ai][bj][m][n] * alpha;
;                         *(f32x4*)(out + o2) = o; sq += (o[0] * o[0] + o[1] * o[1]) + (o[2] * o[2] + o[3] * o[3]);
;                         if (outb) { u32x2 w; w.x = cvt_pk_bf16(o[0], o[1]); w.y = cvt_pk_bf16(o[2], o[3]); *(u32x2*)(outb + o2) = w; } }
;                 sq += __shfl_xor(sq, 16); sq += __shfl_xor(sq, 32);
;                 if (fq == 0) ssq_out[(size_t)row * 32 + u.pn * 4 + wc] = sq; }
.LBB0_1111:
	v_lshl_or_b32 v188, s0, 8, v208
	v_lshl_add_u32 v192, s12, 8, v206
	v_ashrrev_i32_e32 v189, 31, v188
	v_lshlrev_b64 v[220:221], 2, v[188:189]
	v_ashrrev_i32_e32 v193, 31, v192
	v_lshl_add_u64 v[190:191], s[56:57], 0, v[220:221]
	v_lshlrev_b64 v[234:235], 13, v[192:193]
	v_lshl_add_u64 v[196:197], v[190:191], 0, v[234:235]
	v_add_co_u32_e32 v198, vcc, 0x20000, v196
	v_addc_co_u32_e32 v199, vcc, 0, v197, vcc
	v_add_co_u32_e32 v200, vcc, 0x40000, v196
	v_addc_co_u32_e32 v201, vcc, 0, v197, vcc
	v_add_co_u32_e32 v202, vcc, 0x60000, v196
	v_addc_co_u32_e32 v203, vcc, 0, v197, vcc
	v_add_co_u32_e32 v204, vcc, 0x100000, v196
	v_addc_co_u32_e32 v205, vcc, 0, v197, vcc
	v_add_co_u32_e32 v206, vcc, 0x120000, v196
	v_addc_co_u32_e32 v207, vcc, 0, v197, vcc
	v_add_co_u32_e32 v208, vcc, 0x140000, v196
	v_addc_co_u32_e32 v209, vcc, 0, v197, vcc
	v_add_co_u32_e32 v210, vcc, 0x160000, v196
	v_addc_co_u32_e32 v211, vcc, 0, v197, vcc
	v_lshlrev_b64 v[212:213], 7, v[192:193]
	v_lshl_add_u64 v[212:213], s[18:19], 0, v[212:213]
	s_lshl_b32 s28, s0, 4
	s_lshl_b32 s29, s35, 2
	s_add_i32 s28, s28, s29
	s_mov_b32 s29, 0
	v_lshl_add_u64 v[212:213], s[28:29], 0, v[212:213]
	global_load_dwordx4 v[128:131], v[196:197], off nt
	global_load_dwordx4 v[132:135], v[196:197], off offset:64 nt
	global_load_dwordx4 v[136:139], v[196:197], off offset:512 nt
	global_load_dwordx4 v[140:143], v[196:197], off offset:576 nt
	global_load_dwordx4 v[144:147], v[198:199], off nt
	global_load_dwordx4 v[148:151], v[198:199], off offset:64 nt
	global_load_dwordx4 v[152:155], v[198:199], off offset:512 nt
	global_load_dwordx4 v[156:159], v[198:199], off offset:576 nt
	global_load_dwordx4 v[160:163], v[200:201], off nt
	global_load_dwordx4 v[164:167], v[200:201], off offset:64 nt
	global_load_dwordx4 v[168:171], v[200:201], off offset:512 nt
	global_load_dwordx4 v[172:175], v[200:201], off offset:576 nt
	global_load_dwordx4 v[176:179], v[202:203], off nt
	global_load_dwordx4 v[180:183], v[202:203], off offset:64 nt
	global_load_dwordx4 v[184:187], v[202:203], off offset:512 nt
	global_load_dwordx4 v[188:191], v[202:203], off offset:576 nt
	s_waitcnt vmcnt(12)
	v_pk_fma_f32 v[124:125], v[124:125], 0.5, v[128:129] op_sel_hi:[1,0,1]
	v_pk_fma_f32 v[126:127], v[126:127], 0.5, v[130:131] op_sel_hi:[1,0,1]
	v_pk_fma_f32 v[120:121], v[120:121], 0.5, v[132:133] op_sel_hi:[1,0,1]
	v_pk_fma_f32 v[122:123], v[122:123], 0.5, v[134:135] op_sel_hi:[1,0,1]
	v_pk_fma_f32 v[116:117], v[116:117], 0.5, v[136:137] op_sel_hi:[1,0,1]
	v_pk_fma_f32 v[118:119], v[118:119], 0.5, v[138:139] op_sel_hi:[1,0,1]
	v_pk_fma_f32 v[112:113], v[112:113], 0.5, v[140:141] op_sel_hi:[1,0,1]
	v_pk_fma_f32 v[114:115], v[114:115], 0.5, v[142:143] op_sel_hi:[1,0,1]
	v_mul_f32_e32 v248, v124, v124
	v_mul_f32_e32 v229, v125, v125
	v_fmac_f32_e32 v248, v126, v126
	v_fmac_f32_e32 v229, v127, v127
	v_fmac_f32_e32 v248, v120, v120
	v_fmac_f32_e32 v229, v121, v121
	v_fmac_f32_e32 v248, v122, v122
	v_fmac_f32_e32 v229, v123, v123
	v_fmac_f32_e32 v248, v116, v116
	v_fmac_f32_e32 v229, v117, v117
	v_fmac_f32_e32 v248, v118, v118
	v_fmac_f32_e32 v229, v119, v119
	v_fmac_f32_e32 v248, v112, v112
	v_fmac_f32_e32 v229, v113, v113
	v_fmac_f32_e32 v248, v114, v114
	v_fmac_f32_e32 v229, v115, v115
	v_add_f32_e32 v248, v248, v229
	ds_bpermute_b32 v225, v224, v248
	s_waitcnt vmcnt(8)
	v_pk_fma_f32 v[108:109], v[108:109], 0.5, v[144:145] op_sel_hi:[1,0,1]
	v_pk_fma_f32 v[110:111], v[110:111], 0.5, v[146:147] op_sel_hi:[1,0,1]
	v_pk_fma_f32 v[104:105], v[104:105], 0.5, v[148:149] op_sel_hi:[1,0,1]
	v_pk_fma_f32 v[106:107], v[106:107], 0.5, v[150:151] op_sel_hi:[1,0,1]
	v_pk_fma_f32 v[100:101], v[100:101], 0.5, v[152:153] op_sel_hi:[1,0,1]
	v_pk_fma_f32 v[102:103], v[102:103], 0.5, v[154:155] op_sel_hi:[1,0,1]
	v_pk_fma_f32 v[96:97], v[96:97], 0.5, v[156:157] op_sel_hi:[1,0,1]
	v_pk_fma_f32 v[98:99], v[98:99], 0.5, v[158:159] op_sel_hi:[1,0,1]
	v_mul_f32_e32 v249, v108, v108
	v_mul_f32_e32 v229, v109, v109
	v_fmac_f32_e32 v249, v110, v110
	v_fmac_f32_e32 v229, v111, v111
	v_fmac_f32_e32 v249, v104, v104
	v_fmac_f32_e32 v229, v105, v105
	v_fmac_f32_e32 v249, v106, v106
	v_fmac_f32_e32 v229, v107, v107
	v_fmac_f32_e32 v249, v100, v100
	v_fmac_f32_e32 v229, v101, v101
	v_fmac_f32_e32 v249, v102, v102
	v_fmac_f32_e32 v229, v103, v103
	v_fmac_f32_e32 v249, v96, v96
	v_fmac_f32_e32 v229, v97, v97
	v_fmac_f32_e32 v249, v98, v98
	v_fmac_f32_e32 v229, v99, v99
	v_add_f32_e32 v249, v249, v229
	ds_bpermute_b32 v226, v224, v249
	s_waitcnt vmcnt(4)
	v_pk_fma_f32 v[92:93], v[92:93], 0.5, v[160:161] op_sel_hi:[1,0,1]
	v_pk_fma_f32 v[94:95], v[94:95], 0.5, v[162:163] op_sel_hi:[1,0,1]
	v_pk_fma_f32 v[88:89], v[88:89], 0.5, v[164:165] op_sel_hi:[1,0,1]
	v_pk_fma_f32 v[90:91], v[90:91], 0.5, v[166:167] op_sel_hi:[1,0,1]
	v_pk_fma_f32 v[84:85], v[84:85], 0.5, v[168:169] op_sel_hi:[1,0,1]
	v_pk_fma_f32 v[86:87], v[86:87], 0.5, v[170:171] op_sel_hi:[1,0,1]
	v_pk_fma_f32 v[80:81], v[80:81], 0.5, v[172:173] op_sel_hi:[1,0,1]
	v_pk_fma_f32 v[82:83], v[82:83], 0.5, v[174:175] op_sel_hi:[1,0,1]
	v_mul_f32_e32 v250, v92, v92
	v_mul_f32_e32 v229, v93, v93
	v_fmac_f32_e32 v250, v94, v94
	v_fmac_f32_e32 v229, v95, v95
	v_fmac_f32_e32 v250, v88, v88
	v_fmac_f32_e32 v229, v89, v89
	v_fmac_f32_e32 v250, v90, v90
	v_fmac_f32_e32 v229, v91, v91
	v_fmac_f32_e32 v250, v84, v84
	v_fmac_f32_e32 v229, v85, v85
	v_fmac_f32_e32 v250, v86, v86
	v_fmac_f32_e32 v229, v87, v87
	v_fmac_f32_e32 v250, v80, v80
	v_fmac_f32_e32 v229, v81, v81
	v_fmac_f32_e32 v250, v82, v82
	v_fmac_f32_e32 v229, v83, v83
	v_add_f32_e32 v250, v250, v229
	ds_bpermute_b32 v227, v224, v250
	s_waitcnt vmcnt(0)
; __device__ __forceinline__ unsigned cvt_pk_bf16(float lo, float hi) { f32x2 v = {lo, hi}; bf16x2_t b = __builtin_convertvector(v, bf16x2_t); return __builtin_bit_cast(unsigned, b); }
;     __device__ __forceinline__ void operator()(const f32x4 (&acc)[2][2][4][2], const Unit& u, int wr, int wc, int fr, int fq) const {
;     ...
;                     for (int n = 0; n < 2; ++n) bs[m][bj][n] = *(const f32x4*)(base + (size_t)(row0 + ai * HALF + m * 16) * DMODEL + col0 + bj * HALF + n * 16);
; #pragma unroll
;             for (int m = 0; m < 4; ++m) { const int row = row0 + ai * HALF + m * 16; const size_t off = (size_t)row * DMODEL + col0; float sq = 0.f;
; #pragma unroll
;                 for (int bj = 0; bj < 2; ++bj)
; #pragma unroll
;                     for (int n = 0; n < 2; ++n) { const size_t o2 = off + bj * HALF + n * 16; const f32x4 o = bs[m][bj][n] + acc[ai][bj][m][n] * alpha;
;                         *(f32x4*)(out + o2) = o; sq += (o[0] * o[0] + o[1] * o[1]) + (o[2] * o[2] + o[3] * o[3]);
;                         if (outb) { u32x2 w; w.x = cvt_pk_bf16(o[0], o[1]); w.y = cvt_pk_bf16(o[2], o[3]); *(u32x2*)(outb + o2) = w; } }
;                 sq += __shfl_xor(sq, 16); sq += __shfl_xor(sq, 32);
;                 if (fq == 0) ssq_out[(size_t)row * 32 + u.pn * 4 + wc] = sq; }
	v_pk_fma_f32 v[76:77], v[76:77], 0.5, v[176:177] op_sel_hi:[1,0,1]
	v_pk_fma_f32 v[78:79], v[78:79], 0.5, v[178:179] op_sel_hi:[1,0,1]
	v_pk_fma_f32 v[72:73], v[72:73], 0.5, v[180:181] op_sel_hi:[1,0,1]
	v_pk_fma_f32 v[74:75], v[74:75], 0.5, v[182:183] op_sel_hi:[1,0,1]
	v_pk_fma_f32 v[68:69], v[68:69], 0.5, v[184:185] op_sel_hi:[1,0,1]
	v_pk_fma_f32 v[70:71], v[70:71], 0.5, v[186:187] op_sel_hi:[1,0,1]
	v_pk_fma_f32 v[64:65], v[64:65], 0.5, v[188:189] op_sel_hi:[1,0,1]
	v_pk_fma_f32 v[66:67], v[66:67], 0.5, v[190:191] op_sel_hi:[1,0,1]
	v_mul_f32_e32 v251, v76, v76
	v_mul_f32_e32 v229, v77, v77
	v_fmac_f32_e32 v251, v78, v78
	v_fmac_f32_e32 v229, v79, v79
	v_fmac_f32_e32 v251, v72, v72
	v_fmac_f32_e32 v229, v73, v73
	v_fmac_f32_e32 v251, v74, v74
	v_fmac_f32_e32 v229, v75, v75
	v_fmac_f32_e32 v251, v68, v68
	v_fmac_f32_e32 v229, v69, v69
	v_fmac_f32_e32 v251, v70, v70
	v_fmac_f32_e32 v229, v71, v71
	v_fmac_f32_e32 v251, v64, v64
	v_fmac_f32_e32 v229, v65, v65
	v_fmac_f32_e32 v251, v66, v66
	v_fmac_f32_e32 v229, v67, v67
	v_add_f32_e32 v251, v251, v229
	ds_bpermute_b32 v228, v224, v251
	global_load_dwordx4 v[128:131], v[204:205], off nt
	global_load_dwordx4 v[132:135], v[204:205], off offset:64 nt
	global_load_dwordx4 v[136:139], v[204:205], off offset:512 nt
	global_load_dwordx4 v[140:143], v[204:205], off offset:576 nt
	global_load_dwordx4 v[144:147], v[206:207], off nt
	global_load_dwordx4 v[148:151], v[206:207], off offset:64 nt
	global_load_dwordx4 v[152:155], v[206:207], off offset:512 nt
	global_load_dwordx4 v[156:159], v[206:207], off offset:576 nt
	global_load_dwordx4 v[160:163], v[208:209], off nt
	global_load_dwordx4 v[164:167], v[208:209], off offset:64 nt
	global_load_dwordx4 v[168:171], v[208:209], off offset:512 nt
	global_load_dwordx4 v[172:175], v[208:209], off offset:576 nt
	global_load_dwordx4 v[176:179], v[210:211], off nt
	global_load_dwordx4 v[180:183], v[210:211], off offset:64 nt
	global_load_dwordx4 v[184:187], v[210:211], off offset:512 nt
	global_load_dwordx4 v[188:191], v[210:211], off offset:576 nt
	s_waitcnt lgkmcnt(0)
	v_add_f32_e32 v248, v248, v225
	ds_bpermute_b32 v225, v223, v248
	v_add_f32_e32 v249, v249, v226
	ds_bpermute_b32 v226, v223, v249
	v_add_f32_e32 v250, v250, v227
	ds_bpermute_b32 v227, v223, v250
	v_add_f32_e32 v251, v251, v228
	ds_bpermute_b32 v228, v223, v251
	s_waitcnt lgkmcnt(0)
	v_add_f32_e32 v248, v248, v225
	v_add_f32_e32 v249, v249, v226
	v_add_f32_e32 v250, v250, v227
	v_add_f32_e32 v251, v251, v228
	s_and_saveexec_b64 s[12:13], s[6:7]
	s_cbranch_execz .Lfn_sk0
	global_store_dword v[212:213], v248, off
	v_add_co_u32_e32 v214, vcc, 0x800, v212
	v_addc_co_u32_e32 v215, vcc, 0, v213, vcc
	global_store_dword v[214:215], v249, off
	v_add_co_u32_e32 v214, vcc, 0x1000, v212
	v_addc_co_u32_e32 v215, vcc, 0, v213, vcc
	global_store_dword v[214:215], v250, off
	v_add_co_u32_e32 v214, vcc, 0x1800, v212
	v_addc_co_u32_e32 v215, vcc, 0, v213, vcc
	global_store_dword v[214:215], v251, off
; __device__ __forceinline__ unsigned cvt_pk_bf16(float lo, float hi) { f32x2 v = {lo, hi}; bf16x2_t b = __builtin_convertvector(v, bf16x2_t); return __builtin_bit_cast(unsigned, b); }
;     __device__ __forceinline__ void operator()(const f32x4 (&acc)[2][2][4][2], const Unit& u, int wr, int wc, int fr, int fq) const {
;     ...
;             for (int m = 0; m < 4; ++m) { const int row = row0 + ai * HALF + m * 16; const size_t off = (size_t)row * DMODEL + col0; float sq = 0.f;
; #pragma unroll
;                 for (int bj = 0; bj < 2; ++bj)
; #pragma unroll
;                     for (int n = 0; n < 2; ++n) { const size_t o2 = off + bj * HALF + n * 16; const f32x4 o = bs[m][bj][n] + acc[ai][bj][m][n] * alpha;
;                         *(f32x4*)(out + o2) = o; sq += (o[0] * o[0] + o[1] * o[1]) + (o[2] * o[2] + o[3] * o[3]);
;                         if (outb) { u32x2 w; w.x = cvt_pk_bf16(o[0], o[1]); w.y = cvt_pk_bf16(o[2], o[3]); *(u32x2*)(outb + o2) = w; } }
;                 sq += __shfl_xor(sq, 16); sq += __shfl_xor(sq, 32);
;                 if (fq == 0) ssq_out[(size_t)row * 32 + u.pn * 4 + wc] = sq; }
.Lfn_sk0:
	s_or_b64 exec, exec, s[12:13]
	s_waitcnt vmcnt(12)
	v_pk_fma_f32 v[60:61], v[60:61], 0.5, v[128:129] op_sel_hi:[1,0,1]
	v_pk_fma_f32 v[62:63], v[62:63], 0.5, v[130:131] op_sel_hi:[1,0,1]
	v_pk_fma_f32 v[56:57], v[56:57], 0.5, v[132:133] op_sel_hi:[1,0,1]
	v_pk_fma_f32 v[58:59], v[58:59], 0.5, v[134:135] op_sel_hi:[1,0,1]
	v_pk_fma_f32 v[52:53], v[52:53], 0.5, v[136:137] op_sel_hi:[1,0,1]
	v_pk_fma_f32 v[54:55], v[54:55], 0.5, v[138:139] op_sel_hi:[1,0,1]
	v_pk_fma_f32 v[48:49], v[48:49], 0.5, v[140:141] op_sel_hi:[1,0,1]
	v_pk_fma_f32 v[50:51], v[50:51], 0.5, v[142:143] op_sel_hi:[1,0,1]
	v_mul_f32_e32 v248, v60, v60
	v_mul_f32_e32 v229, v61, v61
	v_fmac_f32_e32 v248, v62, v62
	v_fmac_f32_e32 v229, v63, v63
	v_fmac_f32_e32 v248, v56, v56
	v_fmac_f32_e32 v229, v57, v57
	v_fmac_f32_e32 v248, v58, v58
	v_fmac_f32_e32 v229, v59, v59
	v_fmac_f32_e32 v248, v52, v52
	v_fmac_f32_e32 v229, v53, v53
	v_fmac_f32_e32 v248, v54, v54
	v_fmac_f32_e32 v229, v55, v55
	v_fmac_f32_e32 v248, v48, v48
	v_fmac_f32_e32 v229, v49, v49
	v_fmac_f32_e32 v248, v50, v50
	v_fmac_f32_e32 v229, v51, v51
	v_add_f32_e32 v248, v248, v229
	ds_bpermute_b32 v225, v224, v248
	s_waitcnt vmcnt(8)
	v_pk_fma_f32 v[44:45], v[44:45], 0.5, v[144:145] op_sel_hi:[1,0,1]
	v_pk_fma_f32 v[46:47], v[46:47], 0.5, v[146:147] op_sel_hi:[1,0,1]
	v_pk_fma_f32 v[40:41], v[40:41], 0.5, v[148:149] op_sel_hi:[1,0,1]
	v_pk_fma_f32 v[42:43], v[42:43], 0.5, v[150:151] op_sel_hi:[1,0,1]
	v_pk_fma_f32 v[36:37], v[36:37], 0.5, v[152:153] op_sel_hi:[1,0,1]
	v_pk_fma_f32 v[38:39], v[38:39], 0.5, v[154:155] op_sel_hi:[1,0,1]
	v_pk_fma_f32 v[32:33], v[32:33], 0.5, v[156:157] op_sel_hi:[1,0,1]
	v_pk_fma_f32 v[34:35], v[34:35], 0.5, v[158:159] op_sel_hi:[1,0,1]
	v_mul_f32_e32 v249, v44, v44
	v_mul_f32_e32 v229, v45, v45
	v_fmac_f32_e32 v249, v46, v46
	v_fmac_f32_e32 v229, v47, v47
	v_fmac_f32_e32 v249, v40, v40
	v_fmac_f32_e32 v229, v41, v41
	v_fmac_f32_e32 v249, v42, v42
	v_fmac_f32_e32 v229, v43, v43
	v_fmac_f32_e32 v249, v36, v36
	v_fmac_f32_e32 v229, v37, v37
	v_fmac_f32_e32 v249, v38, v38
	v_fmac_f32_e32 v229, v39, v39
	v_fmac_f32_e32 v249, v32, v32
	v_fmac_f32_e32 v229, v33, v33
	v_fmac_f32_e32 v249, v34, v34
	v_fmac_f32_e32 v229, v35, v35
	v_add_f32_e32 v249, v249, v229
	ds_bpermute_b32 v226, v224, v249
	s_waitcnt vmcnt(4)
	v_pk_fma_f32 v[28:29], v[28:29], 0.5, v[160:161] op_sel_hi:[1,0,1]
	v_pk_fma_f32 v[30:31], v[30:31], 0.5, v[162:163] op_sel_hi:[1,0,1]
	v_pk_fma_f32 v[24:25], v[24:25], 0.5, v[164:165] op_sel_hi:[1,0,1]
	v_pk_fma_f32 v[26:27], v[26:27], 0.5, v[166:167] op_sel_hi:[1,0,1]
	v_pk_fma_f32 v[20:21], v[20:21], 0.5, v[168:169] op_sel_hi:[1,0,1]
	v_pk_fma_f32 v[22:23], v[22:23], 0.5, v[170:171] op_sel_hi:[1,0,1]
	v_pk_fma_f32 v[16:17], v[16:17], 0.5, v[172:173] op_sel_hi:[1,0,1]
	v_pk_fma_f32 v[18:19], v[18:19], 0.5, v[174:175] op_sel_hi:[1,0,1]
	v_mul_f32_e32 v250, v28, v28
	v_mul_f32_e32 v229, v29, v29
	v_fmac_f32_e32 v250, v30, v30
	v_fmac_f32_e32 v229, v31, v31
	v_fmac_f32_e32 v250, v24, v24
	v_fmac_f32_e32 v229, v25, v25
	v_fmac_f32_e32 v250, v26, v26
	v_fmac_f32_e32 v229, v27, v27
	v_fmac_f32_e32 v250, v20, v20
	v_fmac_f32_e32 v229, v21, v21
	v_fmac_f32_e32 v250, v22, v22
	v_fmac_f32_e32 v229, v23, v23
	v_fmac_f32_e32 v250, v16, v16
	v_fmac_f32_e32 v229, v17, v17
	v_fmac_f32_e32 v250, v18, v18
	v_fmac_f32_e32 v229, v19, v19
	v_add_f32_e32 v250, v250, v229
	ds_bpermute_b32 v227, v224, v250
	s_waitcnt vmcnt(0)
	v_pk_fma_f32 v[12:13], v[12:13], 0.5, v[176:177] op_sel_hi:[1,0,1]
	v_pk_fma_f32 v[14:15], v[14:15], 0.5, v[178:179] op_sel_hi:[1,0,1]
	v_pk_fma_f32 v[8:9], v[8:9], 0.5, v[180:181] op_sel_hi:[1,0,1]
	v_pk_fma_f32 v[10:11], v[10:11], 0.5, v[182:183] op_sel_hi:[1,0,1]
	v_pk_fma_f32 v[4:5], v[4:5], 0.5, v[184:185] op_sel_hi:[1,0,1]
	v_pk_fma_f32 v[6:7], v[6:7], 0.5, v[186:187] op_sel_hi:[1,0,1]
	v_pk_fma_f32 v[0:1], v[0:1], 0.5, v[188:189] op_sel_hi:[1,0,1]
	v_pk_fma_f32 v[2:3], v[2:3], 0.5, v[190:191] op_sel_hi:[1,0,1]
	v_mul_f32_e32 v251, v12, v12
	v_mul_f32_e32 v229, v13, v13
	v_fmac_f32_e32 v251, v14, v14
	v_fmac_f32_e32 v229, v15, v15
	v_fmac_f32_e32 v251, v8, v8
	v_fmac_f32_e32 v229, v9, v9
	v_fmac_f32_e32 v251, v10, v10
	v_fmac_f32_e32 v229, v11, v11
	v_fmac_f32_e32 v251, v4, v4
	v_fmac_f32_e32 v229, v5, v5
	v_fmac_f32_e32 v251, v6, v6
	v_fmac_f32_e32 v229, v7, v7
	v_fmac_f32_e32 v251, v0, v0
	v_fmac_f32_e32 v229, v1, v1
	v_fmac_f32_e32 v251, v2, v2
	v_fmac_f32_e32 v229, v3, v3
	v_add_f32_e32 v251, v251, v229
	ds_bpermute_b32 v228, v224, v251
	s_waitcnt lgkmcnt(0)
	v_add_f32_e32 v248, v248, v225
	ds_bpermute_b32 v225, v223, v248
	v_add_f32_e32 v249, v249, v226
	ds_bpermute_b32 v226, v223, v249
	v_add_f32_e32 v250, v250, v227
	ds_bpermute_b32 v227, v223, v250
	v_add_f32_e32 v251, v251, v228
	ds_bpermute_b32 v228, v223, v251
	s_waitcnt lgkmcnt(0)
	v_add_f32_e32 v248, v248, v225
	v_add_f32_e32 v249, v249, v226
	v_add_f32_e32 v250, v250, v227
	v_add_f32_e32 v251, v251, v228
	s_and_saveexec_b64 s[12:13], s[6:7]
	s_cbranch_execz .Lfn_sk1
	v_add_co_u32_e32 v214, vcc, 0x4000, v212
	v_addc_co_u32_e32 v215, vcc, 0, v213, vcc
	global_store_dword v[214:215], v248, off
	v_add_co_u32_e32 v214, vcc, 0x4800, v212
	v_addc_co_u32_e32 v215, vcc, 0, v213, vcc
	global_store_dword v[214:215], v249, off
	v_add_co_u32_e32 v214, vcc, 0x5000, v212
	v_addc_co_u32_e32 v215, vcc, 0, v213, vcc
	global_store_dword v[214:215], v250, off
	v_add_co_u32_e32 v214, vcc, 0x5800, v212
	v_addc_co_u32_e32 v215, vcc, 0, v213, vcc
	global_store_dword v[214:215], v251, off

; __device__ __forceinline__ float row_rstd(const float* ssq, int row) {
;     const f32x4* p = (const f32x4*)(ssq + (size_t)row * 32);
;     float s = 0.f;
; #pragma unroll
;     for (int i = 0; i < 8; ++i) { const f32x4 v = p[i]; s += (v[0] + v[1]) + (v[2] + v[3]); }
;     return __builtin_amdgcn_rsqf(s * (1.0f / DMODEL) + RMS_EPS);
; __global__ void __launch_bounds__(512, 2) mega_fwd(Args a) {
;     ...
;         for (int row = gw; row < M_TOK; row += NGW) {
;             const float rs = row_rstd(SSQ3, row);
;             f32x4* xr = (f32x4*)(XR + (size_t)row * DMODEL) + lane;
;             f32x4 xv[8];
; #pragma unroll
;             for (int j = 0; j < 8; ++j) xv[j] = xr[64 * j];
; #pragma unroll
;             for (int j = 0; j < 8; ++j) xr[64 * j] = xv[j] * rs * gf[64 * j];
.LBB0_1183:
	s_or_b64 exec, exec, s[0:1]
	s_waitcnt lgkmcnt(0)
	v_mov_b32_e32 v0, v222
	s_barrier
	v_mov_b32_e32 v0, v230
	v_mov_b32_e32 v1, v231
	v_mov_b32_e32 v2, v232
	v_mov_b32_e32 v3, v233
	v_mov_b32_e32 v4, v234
	v_mov_b32_e32 v5, v235
	v_mov_b32_e32 v6, v236
	v_mov_b32_e32 v7, v237
	v_mov_b32_e32 v8, v238
	v_mov_b32_e32 v9, v239
	v_mov_b32_e32 v10, v240
	v_mov_b32_e32 v11, v241
	v_mov_b32_e32 v12, v242
	v_mov_b32_e32 v13, v243
	v_mov_b32_e32 v14, v244
	v_mov_b32_e32 v15, v245
	v_mov_b32_e32 v16, v246
	v_mov_b32_e32 v17, v247
	s_add_u32 s98, s58, 0x300000
	s_addc_u32 s99, s59, 0
	v_lshrrev_b32_e32 v248, 4, v222
	v_and_b32_e32 v248, 3, v248
	v_lshlrev_b32_e32 v248, 4, v248
	v_lshl_add_u32 v249, v192, 7, v248
	global_load_dwordx4 v[128:131], v249, s[98:99]
	global_load_dwordx4 v[132:135], v249, s[98:99] offset:64
	s_add_u32 s100, s98, 0x800
	s_addc_u32 s101, s99, 0
	global_load_dwordx4 v[136:139], v249, s[100:101]
	global_load_dwordx4 v[140:143], v249, s[100:101] offset:64
	s_add_u32 s100, s98, 0x1000
	s_addc_u32 s101, s99, 0
	global_load_dwordx4 v[144:147], v249, s[100:101]
	global_load_dwordx4 v[148:151], v249, s[100:101] offset:64
	s_add_u32 s100, s98, 0x1800
	s_addc_u32 s101, s99, 0
	global_load_dwordx4 v[152:155], v249, s[100:101]
	global_load_dwordx4 v[156:159], v249, s[100:101] offset:64
	s_add_u32 s100, s98, 0x4000
	s_addc_u32 s101, s99, 0
	global_load_dwordx4 v[160:163], v249, s[100:101]
	global_load_dwordx4 v[164:167], v249, s[100:101] offset:64
	s_add_u32 s100, s98, 0x4800
	s_addc_u32 s101, s99, 0
	global_load_dwordx4 v[168:171], v249, s[100:101]
	global_load_dwordx4 v[172:175], v249, s[100:101] offset:64
	s_add_u32 s100, s98, 0x5000
	s_addc_u32 s101, s99, 0
	global_load_dwordx4 v[176:179], v249, s[100:101]
	global_load_dwordx4 v[180:183], v249, s[100:101] offset:64
	s_add_u32 s100, s98, 0x5800
	s_addc_u32 s101, s99, 0
	global_load_dwordx4 v[184:187], v249, s[100:101]
	global_load_dwordx4 v[188:191], v249, s[100:101] offset:64
	global_load_dwordx4 v[230:233], v220, s[54:55]
	global_load_dwordx4 v[234:237], v220, s[54:55] offset:64
	global_load_dwordx4 v[238:241], v220, s[54:55] offset:512
	global_load_dwordx4 v[242:245], v220, s[54:55] offset:576
	v_mov_b32_e32 v250, 0x358637bd
	s_waitcnt vmcnt(18)
	v_add_f32_e32 v128, v128, v129
	v_add_f32_e32 v130, v130, v131
	v_add_f32_e32 v132, v132, v133
	v_add_f32_e32 v134, v134, v135
	v_add_f32_e32 v128, v128, v130
	v_add_f32_e32 v132, v132, v134
	v_add_f32_e32 v128, v128, v132
	ds_bpermute_b32 v129, v224, v128
	s_waitcnt vmcnt(16)
	v_add_f32_e32 v136, v136, v137
	v_add_f32_e32 v138, v138, v139
	v_add_f32_e32 v140, v140, v141
	v_add_f32_e32 v142, v142, v143
	v_add_f32_e32 v136, v136, v138
	v_add_f32_e32 v140, v140, v142
	v_add_f32_e32 v136, v136, v140
	ds_bpermute_b32 v137, v224, v136
	s_waitcnt vmcnt(14)
	v_add_f32_e32 v144, v144, v145
	v_add_f32_e32 v146, v146, v147
	v_add_f32_e32 v148, v148, v149
	v_add_f32_e32 v150, v150, v151
	v_add_f32_e32 v144, v144, v146
	v_add_f32_e32 v148, v148, v150
	v_add_f32_e32 v144, v144, v148
	ds_bpermute_b32 v145, v224, v144
	s_waitcnt vmcnt(12)
	v_add_f32_e32 v152, v152, v153
	v_add_f32_e32 v154, v154, v155
	v_add_f32_e32 v156, v156, v157
	v_add_f32_e32 v158, v158, v159
	v_add_f32_e32 v152, v152, v154
	v_add_f32_e32 v156, v156, v158
	v_add_f32_e32 v152, v152, v156
	ds_bpermute_b32 v153, v224, v152
	s_waitcnt vmcnt(10)
	v_add_f32_e32 v160, v160, v161
	v_add_f32_e32 v162, v162, v163
	v_add_f32_e32 v164, v164, v165
	v_add_f32_e32 v166, v166, v167
	v_add_f32_e32 v160, v160, v162
	v_add_f32_e32 v164, v164, v166
	v_add_f32_e32 v160, v160, v164
	ds_bpermute_b32 v161, v224, v160
	s_waitcnt vmcnt(8)
	v_add_f32_e32 v168, v168, v169
	v_add_f32_e32 v170, v170, v171
	v_add_f32_e32 v172, v172, v173
	v_add_f32_e32 v174, v174, v175
	v_add_f32_e32 v168, v168, v170
	v_add_f32_e32 v172, v172, v174
	v_add_f32_e32 v168, v168, v172
	ds_bpermute_b32 v169, v224, v168
	s_waitcnt vmcnt(6)
	v_add_f32_e32 v176, v176, v177
	v_add_f32_e32 v178, v178, v179
	v_add_f32_e32 v180, v180, v181
	v_add_f32_e32 v182, v182, v183
	v_add_f32_e32 v176, v176, v178
	v_add_f32_e32 v180, v180, v182
	v_add_f32_e32 v176, v176, v180
	ds_bpermute_b32 v177, v224, v176
	s_waitcnt vmcnt(4)
	v_add_f32_e32 v184, v184, v185
	v_add_f32_e32 v186, v186, v187
	v_add_f32_e32 v188, v188, v189
	v_add_f32_e32 v190, v190, v191
	v_add_f32_e32 v184, v184, v186
	v_add_f32_e32 v188, v188, v190
	v_add_f32_e32 v184, v184, v188
	ds_bpermute_b32 v185, v224, v184
	s_waitcnt lgkmcnt(0)
	v_add_f32_e32 v128, v128, v129
	ds_bpermute_b32 v129, v223, v128
	v_add_f32_e32 v136, v136, v137
	ds_bpermute_b32 v137, v223, v136
	v_add_f32_e32 v144, v144, v145
	ds_bpermute_b32 v145, v223, v144
	v_add_f32_e32 v152, v152, v153
	ds_bpermute_b32 v153, v223, v152
	v_add_f32_e32 v160, v160, v161
	ds_bpermute_b32 v161, v223, v160
	v_add_f32_e32 v168, v168, v169
	ds_bpermute_b32 v169, v223, v168
	v_add_f32_e32 v176, v176, v177
	ds_bpermute_b32 v177, v223, v176
	v_add_f32_e32 v184, v184, v185
	ds_bpermute_b32 v185, v223, v184
	s_waitcnt lgkmcnt(0)
	v_add_f32_e32 v128, v128, v129
	v_fmamk_f32 v128, v128, 0x3a000000, v250
	v_rsq_f32_e32 v128, v128
	v_add_f32_e32 v136, v136, v137
	v_fmamk_f32 v136, v136, 0x3a000000, v250
	v_rsq_f32_e32 v136, v136
	v_add_f32_e32 v144, v144, v145
	v_fmamk_f32 v144, v144, 0x3a000000, v250
	v_rsq_f32_e32 v144, v144
	v_add_f32_e32 v152, v152, v153
	v_fmamk_f32 v152, v152, 0x3a000000, v250
	v_rsq_f32_e32 v152, v152
	v_add_f32_e32 v160, v160, v161
	v_fmamk_f32 v160, v160, 0x3a000000, v250
	v_rsq_f32_e32 v160, v160
	v_add_f32_e32 v168, v168, v169
	v_fmamk_f32 v168, v168, 0x3a000000, v250
	v_rsq_f32_e32 v168, v168
	v_add_f32_e32 v176, v176, v177
	v_fmamk_f32 v176, v176, 0x3a000000, v250
	v_rsq_f32_e32 v176, v176
	v_add_f32_e32 v184, v184, v185
	v_fmamk_f32 v184, v184, 0x3a000000, v250
	v_rsq_f32_e32 v184, v184
	s_waitcnt vmcnt(0)
;     __device__ __forceinline__ void fused(f32x4 (&acc)[2][2][4][2], const Unit& u, int wr, int wc, int fr, int fq, PG8_LAS unsigned char* lds, int wid, int lane) const {
;     ...
;         for (int ai = 0; ai < 2; ++ai)
; #pragma unroll
;             for (int m = 0; m < 4; ++m) { const int rl = ai * HALF + wr * 64 + m * 16 + fr; const float rs = S[rl]; const size_t off = (size_t)(u.pm * BM + rl) * DMODEL + col0;
; #pragma unroll
;                 for (int bj = 0; bj < 2; ++bj)
; #pragma unroll
;                     for (int n = 0; n < 2; ++n) *(f32x4*)(out + off + bj * HALF + n * 16) = acc[ai][bj][m][n] * rs * gv[bj][n]; }
	s_nop 1
	v_pk_mul_f32 v[124:125], v[128:129], v[124:125] op_sel_hi:[0,1]
	v_pk_mul_f32 v[126:127], v[128:129], v[126:127] op_sel_hi:[0,1]
	v_pk_mul_f32 v[124:125], v[124:125], v[230:231]
	v_pk_mul_f32 v[126:127], v[126:127], v[232:233]
	global_store_dwordx4 v[196:197], v[124:127], off nt
	v_pk_mul_f32 v[120:121], v[128:129], v[120:121] op_sel_hi:[0,1]
	v_pk_mul_f32 v[122:123], v[128:129], v[122:123] op_sel_hi:[0,1]
	v_pk_mul_f32 v[120:121], v[120:121], v[234:235]
	v_pk_mul_f32 v[122:123], v[122:123], v[236:237]
	global_store_dwordx4 v[196:197], v[120:123], off offset:64 nt
	v_pk_mul_f32 v[116:117], v[128:129], v[116:117] op_sel_hi:[0,1]
	v_pk_mul_f32 v[118:119], v[128:129], v[118:119] op_sel_hi:[0,1]
	v_pk_mul_f32 v[116:117], v[116:117], v[238:239]
	v_pk_mul_f32 v[118:119], v[118:119], v[240:241]
	global_store_dwordx4 v[196:197], v[116:119], off offset:512 nt
	v_pk_mul_f32 v[112:113], v[128:129], v[112:113] op_sel_hi:[0,1]
	v_pk_mul_f32 v[114:115], v[128:129], v[114:115] op_sel_hi:[0,1]
	v_pk_mul_f32 v[112:113], v[112:113], v[242:243]
	v_pk_mul_f32 v[114:115], v[114:115], v[244:245]
	global_store_dwordx4 v[196:197], v[112:115], off offset:576 nt
	v_pk_mul_f32 v[108:109], v[136:137], v[108:109] op_sel_hi:[0,1]
	v_pk_mul_f32 v[110:111], v[136:137], v[110:111] op_sel_hi:[0,1]
	v_pk_mul_f32 v[108:109], v[108:109], v[230:231]
	v_pk_mul_f32 v[110:111], v[110:111], v[232:233]
	global_store_dwordx4 v[198:199], v[108:111], off nt
	v_pk_mul_f32 v[104:105], v[136:137], v[104:105] op_sel_hi:[0,1]
	v_pk_mul_f32 v[106:107], v[136:137], v[106:107] op_sel_hi:[0,1]
	v_pk_mul_f32 v[104:105], v[104:105], v[234:235]
	v_pk_mul_f32 v[106:107], v[106:107], v[236:237]
	global_store_dwordx4 v[198:199], v[104:107], off offset:64 nt
	v_pk_mul_f32 v[100:101], v[136:137], v[100:101] op_sel_hi:[0,1]
	v_pk_mul_f32 v[102:103], v[136:137], v[102:103] op_sel_hi:[0,1]
	v_pk_mul_f32 v[100:101], v[100:101], v[238:239]
	v_pk_mul_f32 v[102:103], v[102:103], v[240:241]
	global_store_dwordx4 v[198:199], v[100:103], off offset:512 nt
	v_pk_mul_f32 v[96:97], v[136:137], v[96:97] op_sel_hi:[0,1]
	v_pk_mul_f32 v[98:99], v[136:137], v[98:99] op_sel_hi:[0,1]
	v_pk_mul_f32 v[96:97], v[96:97], v[242:243]
	v_pk_mul_f32 v[98:99], v[98:99], v[244:245]
	global_store_dwordx4 v[198:199], v[96:99], off offset:576 nt
	v_pk_mul_f32 v[92:93], v[144:145], v[92:93] op_sel_hi:[0,1]
	v_pk_mul_f32 v[94:95], v[144:145], v[94:95] op_sel_hi:[0,1]
	v_pk_mul_f32 v[92:93], v[92:93], v[230:231]
	v_pk_mul_f32 v[94:95], v[94:95], v[232:233]
	global_store_dwordx4 v[200:201], v[92:95], off nt
	v_pk_mul_f32 v[88:89], v[144:145], v[88:89] op_sel_hi:[0,1]
	v_pk_mul_f32 v[90:91], v[144:145], v[90:91] op_sel_hi:[0,1]
	v_pk_mul_f32 v[88:89], v[88:89], v[234:235]
	v_pk_mul_f32 v[90:91], v[90:91], v[236:237]
	global_store_dwordx4 v[200:201], v[88:91], off offset:64 nt
	v_pk_mul_f32 v[84:85], v[144:145], v[84:85] op_sel_hi:[0,1]
	v_pk_mul_f32 v[86:87], v[144:145], v[86:87] op_sel_hi:[0,1]
	v_pk_mul_f32 v[84:85], v[84:85], v[238:239]
	v_pk_mul_f32 v[86:87], v[86:87], v[240:241]
	global_store_dwordx4 v[200:201], v[84:87], off offset:512 nt
	v_pk_mul_f32 v[80:81], v[144:145], v[80:81] op_sel_hi:[0,1]
	v_pk_mul_f32 v[82:83], v[144:145], v[82:83] op_sel_hi:[0,1]
	v_pk_mul_f32 v[80:81], v[80:81], v[242:243]
	v_pk_mul_f32 v[82:83], v[82:83], v[244:245]
	global_store_dwordx4 v[200:201], v[80:83], off offset:576 nt
	v_pk_mul_f32 v[76:77], v[152:153], v[76:77] op_sel_hi:[0,1]
	v_pk_mul_f32 v[78:79], v[152:153], v[78:79] op_sel_hi:[0,1]
	v_pk_mul_f32 v[76:77], v[76:77], v[230:231]
	v_pk_mul_f32 v[78:79], v[78:79], v[232:233]
	global_store_dwordx4 v[202:203], v[76:79], off nt
	v_pk_mul_f32 v[72:73], v[152:153], v[72:73] op_sel_hi:[0,1]
	v_pk_mul_f32 v[74:75], v[152:153], v[74:75] op_sel_hi:[0,1]
	v_pk_mul_f32 v[72:73], v[72:73], v[234:235]
	v_pk_mul_f32 v[74:75], v[74:75], v[236:237]
	global_store_dwordx4 v[202:203], v[72:75], off offset:64 nt
	v_pk_mul_f32 v[68:69], v[152:153], v[68:69] op_sel_hi:[0,1]
	v_pk_mul_f32 v[70:71], v[152:153], v[70:71] op_sel_hi:[0,1]
	v_pk_mul_f32 v[68:69], v[68:69], v[238:239]
	v_pk_mul_f32 v[70:71], v[70:71], v[240:241]
	global_store_dwordx4 v[202:203], v[68:71], off offset:512 nt
	v_pk_mul_f32 v[64:65], v[152:153], v[64:65] op_sel_hi:[0,1]
	v_pk_mul_f32 v[66:67], v[152:153], v[66:67] op_sel_hi:[0,1]
	v_pk_mul_f32 v[64:65], v[64:65], v[242:243]
;     __device__ __forceinline__ void fused(f32x4 (&acc)[2][2][4][2], const Unit& u, int wr, int wc, int fr, int fq, PG8_LAS unsigned char* lds, int wid, int lane) const {
;     ...
;         for (int ai = 0; ai < 2; ++ai)
; #pragma unroll
;             for (int m = 0; m < 4; ++m) { const int rl = ai * HALF + wr * 64 + m * 16 + fr; const float rs = S[rl]; const size_t off = (size_t)(u.pm * BM + rl) * DMODEL + col0;
; #pragma unroll
;                 for (int bj = 0; bj < 2; ++bj)
; #pragma unroll
;                     for (int n = 0; n < 2; ++n) *(f32x4*)(out + off + bj * HALF + n * 16) = acc[ai][bj][m][n] * rs * gv[bj][n]; }
	v_pk_mul_f32 v[66:67], v[66:67], v[244:245]
	global_store_dwordx4 v[202:203], v[64:67], off offset:576 nt
	v_pk_mul_f32 v[60:61], v[160:161], v[60:61] op_sel_hi:[0,1]
	v_pk_mul_f32 v[62:63], v[160:161], v[62:63] op_sel_hi:[0,1]
	v_pk_mul_f32 v[60:61], v[60:61], v[230:231]
	v_pk_mul_f32 v[62:63], v[62:63], v[232:233]
	global_store_dwordx4 v[204:205], v[60:63], off nt
	v_pk_mul_f32 v[56:57], v[160:161], v[56:57] op_sel_hi:[0,1]
	v_pk_mul_f32 v[58:59], v[160:161], v[58:59] op_sel_hi:[0,1]
	v_pk_mul_f32 v[56:57], v[56:57], v[234:235]
	v_pk_mul_f32 v[58:59], v[58:59], v[236:237]
	global_store_dwordx4 v[204:205], v[56:59], off offset:64 nt
	v_pk_mul_f32 v[52:53], v[160:161], v[52:53] op_sel_hi:[0,1]
	v_pk_mul_f32 v[54:55], v[160:161], v[54:55] op_sel_hi:[0,1]
	v_pk_mul_f32 v[52:53], v[52:53], v[238:239]
	v_pk_mul_f32 v[54:55], v[54:55], v[240:241]
	global_store_dwordx4 v[204:205], v[52:55], off offset:512 nt
	v_pk_mul_f32 v[48:49], v[160:161], v[48:49] op_sel_hi:[0,1]
	v_pk_mul_f32 v[50:51], v[160:161], v[50:51] op_sel_hi:[0,1]
	v_pk_mul_f32 v[48:49], v[48:49], v[242:243]
	v_pk_mul_f32 v[50:51], v[50:51], v[244:245]
	global_store_dwordx4 v[204:205], v[48:51], off offset:576 nt
	v_pk_mul_f32 v[44:45], v[168:169], v[44:45] op_sel_hi:[0,1]
	v_pk_mul_f32 v[46:47], v[168:169], v[46:47] op_sel_hi:[0,1]
	v_pk_mul_f32 v[44:45], v[44:45], v[230:231]
	v_pk_mul_f32 v[46:47], v[46:47], v[232:233]
	global_store_dwordx4 v[206:207], v[44:47], off nt
	v_pk_mul_f32 v[40:41], v[168:169], v[40:41] op_sel_hi:[0,1]
	v_pk_mul_f32 v[42:43], v[168:169], v[42:43] op_sel_hi:[0,1]
	v_pk_mul_f32 v[40:41], v[40:41], v[234:235]
	v_pk_mul_f32 v[42:43], v[42:43], v[236:237]
	global_store_dwordx4 v[206:207], v[40:43], off offset:64 nt
	v_pk_mul_f32 v[36:37], v[168:169], v[36:37] op_sel_hi:[0,1]
	v_pk_mul_f32 v[38:39], v[168:169], v[38:39] op_sel_hi:[0,1]
	v_pk_mul_f32 v[36:37], v[36:37], v[238:239]
	v_pk_mul_f32 v[38:39], v[38:39], v[240:241]
	global_store_dwordx4 v[206:207], v[36:39], off offset:512 nt
	v_pk_mul_f32 v[32:33], v[168:169], v[32:33] op_sel_hi:[0,1]
	v_pk_mul_f32 v[34:35], v[168:169], v[34:35] op_sel_hi:[0,1]
	v_pk_mul_f32 v[32:33], v[32:33], v[242:243]
	v_pk_mul_f32 v[34:35], v[34:35], v[244:245]
	global_store_dwordx4 v[206:207], v[32:35], off offset:576 nt
	v_pk_mul_f32 v[28:29], v[176:177], v[28:29] op_sel_hi:[0,1]
	v_pk_mul_f32 v[30:31], v[176:177], v[30:31] op_sel_hi:[0,1]
	v_pk_mul_f32 v[28:29], v[28:29], v[230:231]
	v_pk_mul_f32 v[30:31], v[30:31], v[232:233]
	global_store_dwordx4 v[208:209], v[28:31], off nt
	v_pk_mul_f32 v[24:25], v[176:177], v[24:25] op_sel_hi:[0,1]
	v_pk_mul_f32 v[26:27], v[176:177], v[26:27] op_sel_hi:[0,1]
	v_pk_mul_f32 v[24:25], v[24:25], v[234:235]
	v_pk_mul_f32 v[26:27], v[26:27], v[236:237]
	global_store_dwordx4 v[208:209], v[24:27], off offset:64 nt
	v_pk_mul_f32 v[20:21], v[176:177], v[20:21] op_sel_hi:[0,1]
	v_pk_mul_f32 v[22:23], v[176:177], v[22:23] op_sel_hi:[0,1]
	v_pk_mul_f32 v[20:21], v[20:21], v[238:239]
	v_pk_mul_f32 v[22:23], v[22:23], v[240:241]
	global_store_dwordx4 v[208:209], v[20:23], off offset:512 nt
	v_pk_mul_f32 v[16:17], v[176:177], v[16:17] op_sel_hi:[0,1]
	v_pk_mul_f32 v[18:19], v[176:177], v[18:19] op_sel_hi:[0,1]
	v_pk_mul_f32 v[16:17], v[16:17], v[242:243]
	v_pk_mul_f32 v[18:19], v[18:19], v[244:245]
	global_store_dwordx4 v[208:209], v[16:19], off offset:576 nt
	v_pk_mul_f32 v[12:13], v[184:185], v[12:13] op_sel_hi:[0,1]
	v_pk_mul_f32 v[14:15], v[184:185], v[14:15] op_sel_hi:[0,1]
	v_pk_mul_f32 v[12:13], v[12:13], v[230:231]
	v_pk_mul_f32 v[14:15], v[14:15], v[232:233]
	global_store_dwordx4 v[210:211], v[12:15], off nt
	v_pk_mul_f32 v[8:9], v[184:185], v[8:9] op_sel_hi:[0,1]
	v_pk_mul_f32 v[10:11], v[184:185], v[10:11] op_sel_hi:[0,1]
	v_pk_mul_f32 v[8:9], v[8:9], v[234:235]
	v_pk_mul_f32 v[10:11], v[10:11], v[236:237]
	global_store_dwordx4 v[210:211], v[8:11], off offset:64 nt
	v_pk_mul_f32 v[4:5], v[184:185], v[4:5] op_sel_hi:[0,1]
	v_pk_mul_f32 v[6:7], v[184:185], v[6:7] op_sel_hi:[0,1]
	v_pk_mul_f32 v[4:5], v[4:5], v[238:239]
	v_pk_mul_f32 v[6:7], v[6:7], v[240:241]
	global_store_dwordx4 v[210:211], v[4:7], off offset:512 nt
	v_pk_mul_f32 v[0:1], v[184:185], v[0:1] op_sel_hi:[0,1]
	v_pk_mul_f32 v[2:3], v[184:185], v[2:3] op_sel_hi:[0,1]
	v_pk_mul_f32 v[0:1], v[0:1], v[242:243]
	v_pk_mul_f32 v[2:3], v[2:3], v[244:245]
	global_store_dwordx4 v[210:211], v[0:3], off offset:576 nt
